# v108 plus DA softmax with packed subtract, in-place exp2, tree sums and no deferred tile sum (fewer VALU instructions, same math order per element except sum association)
# baseline (speedup 1.0000x reference)
; __device__ __forceinline__ unsigned cvtpk(float lo, float hi) { f32x2_t v = {lo, hi}; bf16x2_t b = __builtin_convertvector(v, bf16x2_t); return __builtin_bit_cast(unsigned, b); }
; #define SBAR() __builtin_amdgcn_sched_barrier(0)
; template <bool ISSUE> ...
;     ...
;     const float off = mref - cb;
;     s0 = s0 - off; s1 = s1 - off;
; #pragma unroll
;     for (int r = 0; r < 16; ++r) { s0[r] = __builtin_amdgcn_exp2f(s0[r]); s1[r] = __builtin_amdgcn_exp2f(s1[r]); }
;     {
;         const f32x16 sm = s0 + s1;
;         lsum += ((sm[0] + sm[1]) + (sm[2] + sm[3])) + ((sm[4] + sm[5]) + (sm[6] + sm[7])) + (((sm[8] + sm[9]) + (sm[10] + sm[11])) + ((sm[12] + sm[13]) + (sm[14] + sm[15])));
;     }
;     bf16x8 p[4];
;     {
;         u32x4 w;
;         w.x = cvtpk(s0[0], s0[1]); w.y = cvtpk(s0[2], s0[3]); w.z = cvtpk(s0[4], s0[5]); w.w = cvtpk(s0[6], s0[7]); p[0] = __builtin_bit_cast(bf16x8, w);
;         w.x = cvtpk(s0[8], s0[9]); w.y = cvtpk(s0[10], s0[11]); w.z = cvtpk(s0[12], s0[13]); w.w = cvtpk(s0[14], s0[15]); p[1] = __builtin_bit_cast(bf16x8, w);
;         w.x = cvtpk(s1[0], s1[1]); w.y = cvtpk(s1[2], s1[3]); w.z = cvtpk(s1[4], s1[5]); w.w = cvtpk(s1[6], s1[7]); p[2] = __builtin_bit_cast(bf16x8, w);
;         w.x = cvtpk(s1[8], s1[9]); w.y = cvtpk(s1[10], s1[11]); w.z = cvtpk(s1[12], s1[13]); w.w = cvtpk(s1[14], s1[15]); p[3] = __builtin_bit_cast(bf16x8, w);
;     }
;     v_reads(vb, lds, vaddr, vb_ + 4096);
;     SBAR();
;     pv_rest<128>(o, p, va, vb, lds, vaddr, vb_);
; __device__ __forceinline__ void flash_da2(LAS unsigned char* lds, const bf16* __restrict__ Qw, const bf16* __restrict__ Kb, const bf16* __restrict__ VTb,
;                                           int NT, int qpos_w, f32x16 (&o)[4], float& mref, float& lsum) {
;     ...
;     for (int t = 0; t < NT; t += 2) {
;         da_tile<true>(lds, t, NT, qpos_w, r32, hi, qf, kaddr, vaddr, ksrc, vsrc, kdst, vdst, cls_cur, cb, o, mref, lsum);
;         da_tile<false>(lds, t + 1, NT, qpos_w, r32, hi, qf, kaddr, vaddr, ksrc, vsrc, kdst, vdst, cls_cur, cb, o, mref, lsum);
;         asm volatile("s_waitcnt vmcnt(0) lgkmcnt(0)\n\ts_barrier" ::: "memory");
;     }
.LBB0_427:
	v_sub_f32_e32 v14, v225, v224
	v_pk_add_f32 v[80:81], v[80:81], v[14:15] op_sel_hi:[1,0]
	v_pk_add_f32 v[82:83], v[82:83], v[14:15] op_sel_hi:[1,0]
	v_pk_add_f32 v[84:85], v[84:85], v[14:15] op_sel_hi:[1,0]
	v_pk_add_f32 v[86:87], v[86:87], v[14:15] op_sel_hi:[1,0]
	v_pk_add_f32 v[88:89], v[88:89], v[14:15] op_sel_hi:[1,0]
	v_pk_add_f32 v[90:91], v[90:91], v[14:15] op_sel_hi:[1,0]
	v_pk_add_f32 v[92:93], v[92:93], v[14:15] op_sel_hi:[1,0]
	v_pk_add_f32 v[94:95], v[94:95], v[14:15] op_sel_hi:[1,0]
	v_pk_add_f32 v[96:97], v[96:97], v[14:15] op_sel_hi:[1,0]
	v_pk_add_f32 v[98:99], v[98:99], v[14:15] op_sel_hi:[1,0]
	v_pk_add_f32 v[100:101], v[100:101], v[14:15] op_sel_hi:[1,0]
	v_pk_add_f32 v[102:103], v[102:103], v[14:15] op_sel_hi:[1,0]
	v_pk_add_f32 v[104:105], v[104:105], v[14:15] op_sel_hi:[1,0]
	v_pk_add_f32 v[106:107], v[106:107], v[14:15] op_sel_hi:[1,0]
	v_pk_add_f32 v[108:109], v[108:109], v[14:15] op_sel_hi:[1,0]
	v_pk_add_f32 v[110:111], v[110:111], v[14:15] op_sel_hi:[1,0]
	v_exp_f32_e32 v80, v80
	v_exp_f32_e32 v81, v81
	v_exp_f32_e32 v82, v82
	v_exp_f32_e32 v83, v83
	v_exp_f32_e32 v84, v84
	v_exp_f32_e32 v85, v85
	v_exp_f32_e32 v86, v86
	v_exp_f32_e32 v87, v87
	v_exp_f32_e32 v88, v88
	v_exp_f32_e32 v89, v89
	v_exp_f32_e32 v90, v90
	v_exp_f32_e32 v91, v91
	v_exp_f32_e32 v92, v92
	v_exp_f32_e32 v93, v93
	v_exp_f32_e32 v94, v94
	v_exp_f32_e32 v95, v95
	v_exp_f32_e32 v96, v96
	v_exp_f32_e32 v97, v97
	v_exp_f32_e32 v98, v98
	v_exp_f32_e32 v99, v99
	v_exp_f32_e32 v100, v100
	v_exp_f32_e32 v101, v101
	v_exp_f32_e32 v102, v102
	v_exp_f32_e32 v103, v103
	v_exp_f32_e32 v104, v104
	v_exp_f32_e32 v105, v105
	v_exp_f32_e32 v106, v106
	v_exp_f32_e32 v107, v107
	v_exp_f32_e32 v108, v108
	v_exp_f32_e32 v109, v109
	v_exp_f32_e32 v110, v110
	v_exp_f32_e32 v111, v111
	v_pk_add_f32 v[168:169], v[80:81], v[82:83]
	v_pk_add_f32 v[170:171], v[84:85], v[86:87]
	v_pk_add_f32 v[172:173], v[88:89], v[90:91]
	v_pk_add_f32 v[174:175], v[92:93], v[94:95]
	v_pk_add_f32 v[176:177], v[96:97], v[98:99]
	v_pk_add_f32 v[178:179], v[100:101], v[102:103]
	v_pk_add_f32 v[180:181], v[104:105], v[106:107]
	v_pk_add_f32 v[182:183], v[108:109], v[110:111]
	v_pk_add_f32 v[168:169], v[168:169], v[170:171]
	v_pk_add_f32 v[172:173], v[172:173], v[174:175]
	v_pk_add_f32 v[176:177], v[176:177], v[178:179]
	v_pk_add_f32 v[180:181], v[180:181], v[182:183]
	v_pk_add_f32 v[168:169], v[168:169], v[172:173]
	v_pk_add_f32 v[176:177], v[176:177], v[180:181]
	v_pk_add_f32 v[168:169], v[168:169], v[176:177]
	v_add_f32_e32 v168, v168, v169
	v_cvt_pk_bf16_f32 v164, v80, v81
	v_cvt_pk_bf16_f32 v165, v82, v83
	v_cvt_pk_bf16_f32 v166, v84, v85
	v_cvt_pk_bf16_f32 v167, v86, v87
	v_cvt_pk_bf16_f32 v80, v96, v97
	v_cvt_pk_bf16_f32 v81, v98, v99
	v_cvt_pk_bf16_f32 v82, v100, v101
	v_cvt_pk_bf16_f32 v83, v102, v103
	v_cvt_pk_bf16_f32 v84, v104, v105
	v_cvt_pk_bf16_f32 v85, v106, v107
	v_cvt_pk_bf16_f32 v86, v108, v109
	v_cvt_pk_bf16_f32 v87, v110, v111
	v_add_f32_e32 v0, v0, v168
	v_cvt_pk_bf16_f32 v108, v88, v89
	v_cvt_pk_bf16_f32 v109, v90, v91
	v_cvt_pk_bf16_f32 v110, v92, v93
	v_cvt_pk_bf16_f32 v111, v94, v95
	ds_read_b128 v[92:95], v136 offset:36864
	ds_read_b128 v[96:99], v137 offset:36864
	ds_read_b128 v[100:103], v138 offset:36864
	ds_read_b128 v[104:107], v139 offset:36864
	s_waitcnt lgkmcnt(7)
	v_mfma_f32_32x32x16_bf16 v[64:79], v[6:9], v[80:83], v[64:79]
	s_waitcnt lgkmcnt(6)
	v_mfma_f32_32x32x16_bf16 v[64:79], v[2:5], v[84:87], v[64:79]
	s_waitcnt lgkmcnt(5)
	v_mfma_f32_32x32x16_bf16 v[64:79], v[10:13], v[164:167], v[64:79]
	s_waitcnt lgkmcnt(4)
	v_mfma_f32_32x32x16_bf16 v[64:79], v[128:131], v[108:111], v[64:79]
	ds_read_b128 v[2:5], v136 offset:40960
	ds_read_b128 v[6:9], v137 offset:40960
	ds_read_b128 v[10:13], v138 offset:40960
	ds_read_b128 v[128:131], v139 offset:40960
	s_waitcnt lgkmcnt(7)
	v_mfma_f32_32x32x16_bf16 v[48:63], v[92:95], v[80:83], v[48:63]
	s_waitcnt lgkmcnt(6)
	v_mfma_f32_32x32x16_bf16 v[48:63], v[96:99], v[84:87], v[48:63]
	s_waitcnt lgkmcnt(5)
	v_mfma_f32_32x32x16_bf16 v[48:63], v[100:103], v[164:167], v[48:63]
	s_waitcnt lgkmcnt(4)
	v_mfma_f32_32x32x16_bf16 v[48:63], v[104:107], v[108:111], v[48:63]
	ds_read_b128 v[92:95], v136 offset:45056
	ds_read_b128 v[96:99], v137 offset:45056
	ds_read_b128 v[100:103], v138 offset:45056
	ds_read_b128 v[104:107], v139 offset:45056
	s_waitcnt lgkmcnt(7)
	v_mfma_f32_32x32x16_bf16 v[32:47], v[2:5], v[80:83], v[32:47]
	s_waitcnt lgkmcnt(6)
	v_mfma_f32_32x32x16_bf16 v[32:47], v[6:9], v[84:87], v[32:47]
	s_waitcnt lgkmcnt(5)
	v_mfma_f32_32x32x16_bf16 v[32:47], v[10:13], v[164:167], v[32:47]
	s_waitcnt lgkmcnt(4)
	v_mfma_f32_32x32x16_bf16 v[32:47], v[128:131], v[108:111], v[32:47]
	s_waitcnt lgkmcnt(3)
	v_mfma_f32_32x32x16_bf16 v[16:31], v[92:95], v[80:83], v[16:31]
	s_waitcnt vmcnt(0) lgkmcnt(0)
	s_barrier
	s_add_i32 s8, s8, 2
	s_mov_b64 s[62:63], 0x8000
	s_addk_i32 s53, 0x80
	v_lshl_add_u64 v[160:161], v[160:161], 0, s[62:63]
	v_lshl_add_u64 v[162:163], v[162:163], 0, s[40:41]
	v_add_u32_e32 v223, 0x200, v223
	s_waitcnt lgkmcnt(2)
	v_mfma_f32_32x32x16_bf16 v[16:31], v[96:99], v[84:87], v[16:31]
	s_cmp_lt_u32 s66, s90
	s_waitcnt lgkmcnt(1)
	v_mfma_f32_32x32x16_bf16 v[16:31], v[100:103], v[164:167], v[16:31]
	s_waitcnt lgkmcnt(0)
	v_mfma_f32_32x32x16_bf16 v[16:31], v[104:107], v[108:111], v[16:31]
	s_cbranch_scc0 .LBB0_450

; #define LAS __attribute__((address_space(3)))
; __device__ __forceinline__ unsigned cvtpk(float lo, float hi) { f32x2_t v = {lo, hi}; bf16x2_t b = __builtin_convertvector(v, bf16x2_t); return __builtin_bit_cast(unsigned, b); }
; #define SBAR() __builtin_amdgcn_sched_barrier(0)
; template <bool ISSUE> ...
;     ...
;     const unsigned kb_ = (unsigned)(t & 3) * 8192, vb_ = (unsigned)(t & 3) * 16384;
;     bf16x8 kf[8];
; #pragma unroll
;     for (int d0 = 0; d0 < 4; ++d0) { kf[2 * d0] = *(const LAS bf16x8*)(lds + kaddr[d0] + kb_); kf[2 * d0 + 1] = *(const LAS bf16x8*)(lds + kaddr[d0] + kb_ + 4096); }
;     SBAR();
;     const int kt = t * 64;
;     const int rpmin = kt - (qpos_w + 31), rpmax = kt + 63 - qpos_w;
;     const int cls = (rpmax <= -91 ? 1 : (rpmin >= 91 ? 2 : 0));
;     if (cls != cls_cur) { cls_cur = cls; cb = (cls == 0) ? 0.f : (cls == 1 ? bt[0] : bt[258]); }
;     ...
;     const float off = mref - cb;
;     s0 = s0 - off; s1 = s1 - off;
; #pragma unroll
;     for (int r = 0; r < 16; ++r) { s0[r] = __builtin_amdgcn_exp2f(s0[r]); s1[r] = __builtin_amdgcn_exp2f(s1[r]); }
;     {
;         const f32x16 sm = s0 + s1;
;         lsum += ((sm[0] + sm[1]) + (sm[2] + sm[3])) + ((sm[4] + sm[5]) + (sm[6] + sm[7])) + (((sm[8] + sm[9]) + (sm[10] + sm[11])) + ((sm[12] + sm[13]) + (sm[14] + sm[15])));
;     }
;     bf16x8 p[4];
;     {
;         u32x4 w;
;         w.x = cvtpk(s0[0], s0[1]); w.y = cvtpk(s0[2], s0[3]); w.z = cvtpk(s0[4], s0[5]); w.w = cvtpk(s0[6], s0[7]); p[0] = __builtin_bit_cast(bf16x8, w);
;         w.x = cvtpk(s0[8], s0[9]); w.y = cvtpk(s0[10], s0[11]); w.z = cvtpk(s0[12], s0[13]); w.w = cvtpk(s0[14], s0[15]); p[1] = __builtin_bit_cast(bf16x8, w);
;         w.x = cvtpk(s1[0], s1[1]); w.y = cvtpk(s1[2], s1[3]); w.z = cvtpk(s1[4], s1[5]); w.w = cvtpk(s1[6], s1[7]); p[2] = __builtin_bit_cast(bf16x8, w);
;         w.x = cvtpk(s1[8], s1[9]); w.y = cvtpk(s1[10], s1[11]); w.z = cvtpk(s1[12], s1[13]); w.w = cvtpk(s1[14], s1[15]); p[3] = __builtin_bit_cast(bf16x8, w);
;     }
;     v_reads(vb, lds, vaddr, vb_ + 4096);
;     SBAR();
;     pv_rest<128>(o, p, va, vb, lds, vaddr, vb_);
.LBB0_440:
	v_sub_f32_e32 v14, v225, v224
	v_pk_add_f32 v[80:81], v[80:81], v[14:15] op_sel_hi:[1,0]
	v_pk_add_f32 v[82:83], v[82:83], v[14:15] op_sel_hi:[1,0]
	v_pk_add_f32 v[84:85], v[84:85], v[14:15] op_sel_hi:[1,0]
	v_pk_add_f32 v[86:87], v[86:87], v[14:15] op_sel_hi:[1,0]
	v_pk_add_f32 v[88:89], v[88:89], v[14:15] op_sel_hi:[1,0]
	v_pk_add_f32 v[90:91], v[90:91], v[14:15] op_sel_hi:[1,0]
	v_pk_add_f32 v[92:93], v[92:93], v[14:15] op_sel_hi:[1,0]
	v_pk_add_f32 v[94:95], v[94:95], v[14:15] op_sel_hi:[1,0]
	v_pk_add_f32 v[96:97], v[96:97], v[14:15] op_sel_hi:[1,0]
	v_pk_add_f32 v[98:99], v[98:99], v[14:15] op_sel_hi:[1,0]
	v_pk_add_f32 v[100:101], v[100:101], v[14:15] op_sel_hi:[1,0]
	v_pk_add_f32 v[102:103], v[102:103], v[14:15] op_sel_hi:[1,0]
	v_pk_add_f32 v[104:105], v[104:105], v[14:15] op_sel_hi:[1,0]
	v_pk_add_f32 v[106:107], v[106:107], v[14:15] op_sel_hi:[1,0]
	v_pk_add_f32 v[108:109], v[108:109], v[14:15] op_sel_hi:[1,0]
	v_pk_add_f32 v[110:111], v[110:111], v[14:15] op_sel_hi:[1,0]
	v_exp_f32_e32 v80, v80
	v_exp_f32_e32 v81, v81
	v_exp_f32_e32 v82, v82
	v_exp_f32_e32 v83, v83
	v_exp_f32_e32 v84, v84
	v_exp_f32_e32 v85, v85
	v_exp_f32_e32 v86, v86
	v_exp_f32_e32 v87, v87
	v_exp_f32_e32 v88, v88
	v_exp_f32_e32 v89, v89
	v_exp_f32_e32 v90, v90
	v_exp_f32_e32 v91, v91
	v_exp_f32_e32 v92, v92
	v_exp_f32_e32 v93, v93
	v_exp_f32_e32 v94, v94
	v_exp_f32_e32 v95, v95
	v_exp_f32_e32 v96, v96
	v_exp_f32_e32 v97, v97
	v_exp_f32_e32 v98, v98
	v_exp_f32_e32 v99, v99
	v_exp_f32_e32 v100, v100
	v_exp_f32_e32 v101, v101
	v_exp_f32_e32 v102, v102
	v_exp_f32_e32 v103, v103
	v_exp_f32_e32 v104, v104
	v_exp_f32_e32 v105, v105
	v_exp_f32_e32 v106, v106
	v_exp_f32_e32 v107, v107
	v_exp_f32_e32 v108, v108
	v_exp_f32_e32 v109, v109
	v_exp_f32_e32 v110, v110
	v_exp_f32_e32 v111, v111
	v_pk_add_f32 v[168:169], v[80:81], v[82:83]
	v_pk_add_f32 v[170:171], v[84:85], v[86:87]
	v_pk_add_f32 v[172:173], v[88:89], v[90:91]
	v_pk_add_f32 v[174:175], v[92:93], v[94:95]
	v_pk_add_f32 v[176:177], v[96:97], v[98:99]
	v_pk_add_f32 v[178:179], v[100:101], v[102:103]
	v_pk_add_f32 v[180:181], v[104:105], v[106:107]
	v_pk_add_f32 v[182:183], v[108:109], v[110:111]
	v_pk_add_f32 v[168:169], v[168:169], v[170:171]
	v_pk_add_f32 v[172:173], v[172:173], v[174:175]
	v_pk_add_f32 v[176:177], v[176:177], v[178:179]
	v_pk_add_f32 v[180:181], v[180:181], v[182:183]
	v_pk_add_f32 v[168:169], v[168:169], v[172:173]
	v_pk_add_f32 v[176:177], v[176:177], v[180:181]
	v_pk_add_f32 v[168:169], v[168:169], v[176:177]
	v_add_f32_e32 v168, v168, v169
	v_cvt_pk_bf16_f32 v164, v80, v81
	v_cvt_pk_bf16_f32 v165, v82, v83
	v_cvt_pk_bf16_f32 v166, v84, v85
	v_cvt_pk_bf16_f32 v167, v86, v87
	v_cvt_pk_bf16_f32 v80, v96, v97
	v_cvt_pk_bf16_f32 v81, v98, v99
	v_cvt_pk_bf16_f32 v82, v100, v101
	v_cvt_pk_bf16_f32 v83, v102, v103
	v_cvt_pk_bf16_f32 v84, v104, v105
	v_cvt_pk_bf16_f32 v85, v106, v107
	v_cvt_pk_bf16_f32 v86, v108, v109
	v_cvt_pk_bf16_f32 v87, v110, v111
	v_add_f32_e32 v0, v0, v168
	v_cvt_pk_bf16_f32 v108, v88, v89
	v_cvt_pk_bf16_f32 v109, v90, v91
	v_cvt_pk_bf16_f32 v110, v92, v93
	v_cvt_pk_bf16_f32 v111, v94, v95
	ds_read_b128 v[92:95], v136 offset:36864
	ds_read_b128 v[96:99], v137 offset:36864
	ds_read_b128 v[100:103], v138 offset:36864
	ds_read_b128 v[104:107], v139 offset:36864
	s_waitcnt lgkmcnt(7)
	v_mfma_f32_32x32x16_bf16 v[64:79], v[6:9], v[80:83], v[64:79]
	s_waitcnt lgkmcnt(6)
	v_mfma_f32_32x32x16_bf16 v[64:79], v[2:5], v[84:87], v[64:79]
	s_waitcnt lgkmcnt(5)
	v_mfma_f32_32x32x16_bf16 v[64:79], v[10:13], v[164:167], v[64:79]
	s_waitcnt lgkmcnt(4)
	v_mfma_f32_32x32x16_bf16 v[64:79], v[128:131], v[108:111], v[64:79]
	ds_read_b128 v[2:5], v136 offset:40960
	ds_read_b128 v[6:9], v137 offset:40960
	ds_read_b128 v[10:13], v138 offset:40960
	ds_read_b128 v[128:131], v139 offset:40960
	s_waitcnt lgkmcnt(7)
	v_mfma_f32_32x32x16_bf16 v[48:63], v[92:95], v[80:83], v[48:63]
	s_waitcnt lgkmcnt(6)
	v_mfma_f32_32x32x16_bf16 v[48:63], v[96:99], v[84:87], v[48:63]
	s_waitcnt lgkmcnt(5)
	v_mfma_f32_32x32x16_bf16 v[48:63], v[100:103], v[164:167], v[48:63]
	s_waitcnt lgkmcnt(4)
	v_mfma_f32_32x32x16_bf16 v[48:63], v[104:107], v[108:111], v[48:63]
	ds_read_b128 v[92:95], v136 offset:45056
	ds_read_b128 v[96:99], v137 offset:45056
	ds_read_b128 v[100:103], v138 offset:45056
	ds_read_b128 v[104:107], v139 offset:45056
	s_waitcnt lgkmcnt(7)
	v_mfma_f32_32x32x16_bf16 v[32:47], v[2:5], v[80:83], v[32:47]
	s_waitcnt lgkmcnt(6)
	v_mfma_f32_32x32x16_bf16 v[32:47], v[6:9], v[84:87], v[32:47]
	s_waitcnt lgkmcnt(5)
	v_mfma_f32_32x32x16_bf16 v[32:47], v[10:13], v[164:167], v[32:47]
	s_waitcnt lgkmcnt(4)
	v_mfma_f32_32x32x16_bf16 v[32:47], v[128:131], v[108:111], v[32:47]
	s_waitcnt lgkmcnt(3)
	v_mfma_f32_32x32x16_bf16 v[16:31], v[92:95], v[80:83], v[16:31]
	s_add_i32 s11, s8, -2
	s_and_b32 s11, s11, 3
	s_lshl_b32 s67, s11, 13
	s_add_i32 s70, s67, 0
	v_add_u32_e32 v6, s70, v206
	v_add_u32_e32 v10, s70, v207
	ds_read_b128 v[2:5], v6
	ds_read_b128 v[6:9], v6 offset:4096
	s_waitcnt lgkmcnt(4)
	v_mfma_f32_32x32x16_bf16 v[16:31], v[96:99], v[84:87], v[16:31]
	ds_read_b128 v[144:147], v10
	ds_read_b128 v[136:139], v10 offset:4096
	v_add_u32_e32 v10, s70, v208
	v_add_u32_e32 v80, s70, v209
	ds_read_b128 v[140:143], v10
	ds_read_b128 v[128:131], v10 offset:4096
	ds_read_b128 v[10:13], v80
	ds_read_b128 v[132:135], v80 offset:4096
	s_waitcnt lgkmcnt(9)
	v_mfma_f32_32x32x16_bf16 v[16:31], v[100:103], v[164:167], v[16:31]
	s_waitcnt lgkmcnt(8)
	v_mfma_f32_32x32x16_bf16 v[16:31], v[104:107], v[108:111], v[16:31]
	s_add_i32 s11, s53, 31
	s_cmpk_gt_i32 s53, 0x5a
	s_cselect_b32 s62, 2, 0
	s_cmpk_gt_i32 s11, 0xff66
	s_cselect_b32 s71, s62, 1
	s_cmp_eq_u32 s71, s10
	s_cbranch_scc1 .LBB0_446
	s_cmp_lt_i32 s71, 1
	v_mov_b32_e32 v225, 0
	s_mov_b32 s10, s71
	s_cbranch_scc1 .LBB0_446
	s_cmp_lg_u32 s71, 1
	s_cbranch_scc0 .LBB0_444
	v_mov_b32_e32 v80, s83
	ds_read_b32 v225, v80
	s_mov_b32 s10, 2
	s_cbranch_execz .LBB0_445
	s_branch .LBB0_446

; __device__ __forceinline__ float hmax(float v) { auto rr = __builtin_amdgcn_permlane32_swap(__float_as_uint(v), __float_as_uint(v), false, false); return fmaxf(__uint_as_float(rr[0]), __uint_as_float(rr[1])); }
; __device__ __forceinline__ float max3f(float a, float b, float c) { float r; asm("v_max3_f32 %0, %1, %2, %3" : "=v"(r) : "v"(a), "v"(b), "v"(c)); return r; }
; template <bool ISSUE> ...
;     ...
;     float mx;
;     {
;         float m0 = max3f(s0[0], s0[1], s0[2]), m1 = max3f(s0[8], s0[9], s0[10]), m2 = max3f(s1[0], s1[1], s1[2]), m3 = max3f(s1[8], s1[9], s1[10]);
;         m0 = max3f(m0, s0[3], s0[4]); m1 = max3f(m1, s0[11], s0[12]); m2 = max3f(m2, s1[3], s1[4]); m3 = max3f(m3, s1[11], s1[12]);
;         m0 = max3f(m0, s0[5], s0[6]); m1 = max3f(m1, s0[13], s0[14]); m2 = max3f(m2, s1[5], s1[6]); m3 = max3f(m3, s1[13], s1[14]);
;         m0 = max3f(m0, s0[7], s0[15]); m2 = max3f(m2, s1[7], s1[15]);
;         mx = max3f(max3f(m0, m1, m2), m3, m3);
;     }
;     mx = hmax(mx) + (cb - mref);
;     if (__any(mx > 8.0f)) {
;         const float dl = fmaxf(mx, 0.f);
;         mref += dl;
;         const float f = __builtin_amdgcn_exp2f(-dl);
;         lsum *= f;
; #pragma unroll
;         for (int db = 0; db < 4; ++db) o[db] *= f;
;     }
.Lmx_qno:
	s_nop 7
	s_nop 2
	v_max3_f32 v14, v96, v97, v98
	v_max3_f32 v132, v80, v81, v82
	v_max3_f32 v15, v104, v105, v106
	v_max3_f32 v133, v88, v89, v90
	s_nop 0
	v_max3_f32 v14, v14, v99, v100
	v_max3_f32 v132, v132, v83, v84
	v_max3_f32 v15, v15, v107, v108
	v_max3_f32 v133, v133, v91, v92
	s_nop 0
	v_max3_f32 v14, v14, v101, v102
	v_max3_f32 v132, v132, v85, v86
	v_max3_f32 v15, v15, v109, v110
	v_max3_f32 v133, v133, v93, v94
	s_nop 0
	v_max3_f32 v14, v14, v103, v111
	v_max3_f32 v132, v132, v87, v95
	s_nop 0
	v_max3_f32 v14, v14, v15, v132
	s_nop 0
	v_max3_f32 v14, v14, v133, v133
	s_nop 0
	v_mov_b32_e32 v15, v14
	s_nop 1
	v_permlane32_swap_b32_e32 v14, v15
	v_max_f32_e32 v15, v15, v15
	v_max_f32_e32 v14, v14, v14
	v_max_f32_e32 v14, v14, v15
	v_sub_f32_e32 v15, v225, v224
	v_add_f32_e32 v14, v15, v14
	v_cmp_lt_f32_e32 vcc, s85, v14
	s_cbranch_vccz .LBB0_427
	v_max_f32_e32 v14, v14, v14
	v_max_f32_e32 v15, 0, v14
	v_exp_f32_e64 v14, -v15
	v_add_f32_e32 v224, v224, v15
	v_mul_f32_e32 v0, v0, v14
	v_pk_mul_f32 v[78:79], v[78:79], v[14:15] op_sel_hi:[1,0]
	v_pk_mul_f32 v[76:77], v[76:77], v[14:15] op_sel_hi:[1,0]
	v_pk_mul_f32 v[74:75], v[74:75], v[14:15] op_sel_hi:[1,0]
	v_pk_mul_f32 v[72:73], v[72:73], v[14:15] op_sel_hi:[1,0]
	v_pk_mul_f32 v[70:71], v[70:71], v[14:15] op_sel_hi:[1,0]
	v_pk_mul_f32 v[68:69], v[68:69], v[14:15] op_sel_hi:[1,0]
	v_pk_mul_f32 v[66:67], v[66:67], v[14:15] op_sel_hi:[1,0]
	v_pk_mul_f32 v[64:65], v[64:65], v[14:15] op_sel_hi:[1,0]
	v_pk_mul_f32 v[62:63], v[62:63], v[14:15] op_sel_hi:[1,0]
	v_pk_mul_f32 v[60:61], v[60:61], v[14:15] op_sel_hi:[1,0]
	v_pk_mul_f32 v[58:59], v[58:59], v[14:15] op_sel_hi:[1,0]
	v_pk_mul_f32 v[56:57], v[56:57], v[14:15] op_sel_hi:[1,0]
	v_pk_mul_f32 v[54:55], v[54:55], v[14:15] op_sel_hi:[1,0]
	v_pk_mul_f32 v[52:53], v[52:53], v[14:15] op_sel_hi:[1,0]
	v_pk_mul_f32 v[50:51], v[50:51], v[14:15] op_sel_hi:[1,0]
	v_pk_mul_f32 v[48:49], v[48:49], v[14:15] op_sel_hi:[1,0]
	v_pk_mul_f32 v[46:47], v[46:47], v[14:15] op_sel_hi:[1,0]
	v_pk_mul_f32 v[44:45], v[44:45], v[14:15] op_sel_hi:[1,0]
	v_pk_mul_f32 v[42:43], v[42:43], v[14:15] op_sel_hi:[1,0]
	v_pk_mul_f32 v[40:41], v[40:41], v[14:15] op_sel_hi:[1,0]
	v_pk_mul_f32 v[38:39], v[38:39], v[14:15] op_sel_hi:[1,0]
	v_pk_mul_f32 v[36:37], v[36:37], v[14:15] op_sel_hi:[1,0]
	v_pk_mul_f32 v[34:35], v[34:35], v[14:15] op_sel_hi:[1,0]
	v_pk_mul_f32 v[32:33], v[32:33], v[14:15] op_sel_hi:[1,0]
	v_pk_mul_f32 v[30:31], v[30:31], v[14:15] op_sel_hi:[1,0]
	v_pk_mul_f32 v[28:29], v[28:29], v[14:15] op_sel_hi:[1,0]
	v_pk_mul_f32 v[26:27], v[26:27], v[14:15] op_sel_hi:[1,0]
	v_pk_mul_f32 v[24:25], v[24:25], v[14:15] op_sel_hi:[1,0]
	v_pk_mul_f32 v[22:23], v[22:23], v[14:15] op_sel_hi:[1,0]
	v_pk_mul_f32 v[20:21], v[20:21], v[14:15] op_sel_hi:[1,0]
	v_pk_mul_f32 v[18:19], v[18:19], v[14:15] op_sel_hi:[1,0]
	v_pk_mul_f32 v[16:17], v[16:17], v[14:15] op_sel_hi:[1,0]
	s_branch .LBB0_427
